# scan decay-table staging: 16 loads in flight before LDS writes
# speedup vs baseline: 1.0019x; 1.0019x over previous
; #define LAS __attribute__((address_space(3)))
; #define SCAN_LOAD(uv, cb) do { _Pragma("unroll") for (int i = 0; i < 16; ++i) uv[i] = *(const u32x2*)(ut + (size_t)((cb) + i) * 131072); } while (0)
; __device__ __forceinline__ void scan_task(const Params& p, int l, int j, LAS unsigned char* lds) {
;     ...
;     const u16* ut = (const u16*)(ws + WS_UT) + e; u16* sp = (u16*)(ws + WS_SP) + e;
;     LAS float* dl = (LAS float*)lds;
;     {
;         const float* dsrc = (const float*)(ws + WS_DEC) + h * 128;
; #pragma unroll
;         for (int i = 0; i < 16; ++i) { const int q = tid + i * 512, c = q >> 5, d4 = (q & 31) * 4; *(LAS f32x4*)(dl + c * 128 + d4) = *(const f32x4*)(dsrc + (size_t)c * 512 + d4); }
;     }
;     f32x4 S = (f32x4){0.f, 0.f, 0.f, 0.f};
;     u32x2 uvA[16], uvB[16];
;     ...
;     SCAN_LOAD(uvA, 0);
;     __syncthreads();
.LBB0_770:
	s_andn2_b64 vcc, exec, s[0:1]
	s_cbranch_vccnz .LBB0_592
	v_mov_b32_e32 v9, v200
	v_readlane_b32 s6, v254, 36
	v_lshlrev_b32_e32 v0, 2, v9
	v_lshl_add_u32 v6, s23, 11, v0
	v_ashrrev_i32_e32 v8, 15, v6
	s_waitcnt lgkmcnt(0)
	v_lshlrev_b32_e32 v2, 7, v8
	v_and_b32_e32 v82, 0x7c, v0
	v_ashrrev_i32_e32 v3, 31, v2
	v_readlane_b32 s7, v254, 37
	v_ashrrev_i32_e32 v4, 5, v9
	v_lshlrev_b32_e32 v0, 2, v82
	v_lshl_add_u64 v[2:3], v[2:3], 2, s[6:7]
	v_ashrrev_i32_e32 v5, 31, v4
	v_lshl_add_u64 v[2:3], v[2:3], 0, v[0:1]
	v_lshlrev_b64 v[10:11], 11, v[4:5]
	s_mov_b32 s0, s31
	v_lshl_add_u64 v[10:11], v[2:3], 0, v[10:11]
	v_add_u32_e32 v0, 0, v0
	v_lshl_add_u32 v4, v4, 9, v0
	v_ashrrev_i32_e32 v7, 31, v6
	s_mov_b32 s1, 0x40000
	s_mov_b32 s2, 0x80000
	v_readlane_b32 s6, v252, 37
	v_readlane_b32 s7, v252, 38
	s_mov_b64 s[98:99], 0x8000
	v_mov_b32_e32 v42, v10
	v_mov_b32_e32 v43, v11
	global_load_dwordx4 v[10:13], v[42:43], off
	v_lshl_add_u64 v[42:43], v[42:43], 0, s[98:99]
	global_load_dwordx4 v[14:17], v[42:43], off
	v_lshl_add_u64 v[42:43], v[42:43], 0, s[98:99]
	global_load_dwordx4 v[18:21], v[42:43], off
	v_lshl_add_u64 v[42:43], v[42:43], 0, s[98:99]
	global_load_dwordx4 v[22:25], v[42:43], off
	v_lshl_add_u64 v[42:43], v[42:43], 0, s[98:99]
	global_load_dwordx4 v[26:29], v[42:43], off
	v_lshl_add_u64 v[42:43], v[42:43], 0, s[98:99]
	global_load_dwordx4 v[30:33], v[42:43], off
	v_lshl_add_u64 v[42:43], v[42:43], 0, s[98:99]
	global_load_dwordx4 v[34:37], v[42:43], off
	v_lshl_add_u64 v[42:43], v[42:43], 0, s[98:99]
	global_load_dwordx4 v[38:41], v[42:43], off
	v_lshl_add_u64 v[42:43], v[42:43], 0, s[98:99]
	global_load_dwordx4 v[46:49], v[42:43], off
	v_lshl_add_u64 v[42:43], v[42:43], 0, s[98:99]
	global_load_dwordx4 v[50:53], v[42:43], off
	v_lshl_add_u64 v[42:43], v[42:43], 0, s[98:99]
	global_load_dwordx4 v[54:57], v[42:43], off
	v_lshl_add_u64 v[42:43], v[42:43], 0, s[98:99]
	global_load_dwordx4 v[58:61], v[42:43], off
	v_lshl_add_u64 v[42:43], v[42:43], 0, s[98:99]
	global_load_dwordx4 v[62:65], v[42:43], off
	v_lshl_add_u64 v[42:43], v[42:43], 0, s[98:99]
	global_load_dwordx4 v[66:69], v[42:43], off
	v_lshl_add_u64 v[42:43], v[42:43], 0, s[98:99]
	global_load_dwordx4 v[70:73], v[42:43], off
	v_lshl_add_u64 v[42:43], v[42:43], 0, s[98:99]
	global_load_dwordx4 v[42:45], v[42:43], off
	v_add_u32_e32 v5, 0x10000, v4
	s_waitcnt vmcnt(15)
	ds_write_b128 v4, v[10:13]
	s_waitcnt vmcnt(14)
	ds_write_b128 v4, v[14:17] offset:8192
	s_waitcnt vmcnt(13)
	ds_write_b128 v4, v[18:21] offset:16384
	s_waitcnt vmcnt(12)
	ds_write_b128 v4, v[22:25] offset:24576
	s_waitcnt vmcnt(11)
	ds_write_b128 v4, v[26:29] offset:32768
	s_waitcnt vmcnt(10)
	ds_write_b128 v4, v[30:33] offset:40960
	s_waitcnt vmcnt(9)
	ds_write_b128 v4, v[34:37] offset:49152
	s_waitcnt vmcnt(8)
	ds_write_b128 v4, v[38:41] offset:57344
	s_waitcnt vmcnt(7)
	ds_write_b128 v5, v[46:49]
	s_waitcnt vmcnt(6)
	ds_write_b128 v5, v[50:53] offset:8192
	s_waitcnt vmcnt(5)
	ds_write_b128 v5, v[54:57] offset:16384
	s_waitcnt vmcnt(4)
	ds_write_b128 v5, v[58:61] offset:24576
	s_waitcnt vmcnt(3)
	ds_write_b128 v5, v[62:65] offset:32768
	s_waitcnt vmcnt(2)
	ds_write_b128 v5, v[66:69] offset:40960
	s_waitcnt vmcnt(1)
	ds_write_b128 v5, v[70:73] offset:49152
	s_waitcnt vmcnt(0)
	ds_write_b128 v5, v[42:45] offset:57344
	v_lshlrev_b64 v[2:3], 1, v[6:7]
	v_lshl_add_u64 v[4:5], s[66:67], 0, v[2:3]
	v_add_co_u32_e32 v12, vcc, s1, v4
	global_load_dwordx2 v[10:11], v[4:5], off
	s_nop 0
	v_addc_co_u32_e32 v13, vcc, 0, v5, vcc
	v_add_co_u32_e32 v14, vcc, s2, v4
	s_mov_b32 s2, 0xc0000
	s_nop 0
	v_addc_co_u32_e32 v15, vcc, 0, v5, vcc
	v_add_co_u32_e32 v16, vcc, s2, v4
	s_mov_b32 s2, 0x100000
	s_nop 0
	v_addc_co_u32_e32 v17, vcc, 0, v5, vcc
	v_add_co_u32_e32 v18, vcc, s2, v4
	s_mov_b32 s2, 0x140000
	s_nop 0
	v_addc_co_u32_e32 v19, vcc, 0, v5, vcc
	v_add_co_u32_e32 v20, vcc, s2, v4
	s_mov_b32 s2, 0x180000
	s_nop 0
	v_addc_co_u32_e32 v21, vcc, 0, v5, vcc
	v_add_co_u32_e32 v22, vcc, s2, v4
	s_mov_b32 s2, 0x1c0000
	s_nop 0
	v_addc_co_u32_e32 v23, vcc, 0, v5, vcc
	v_add_co_u32_e32 v24, vcc, s2, v4
	s_mov_b32 s2, 0x200000
	s_nop 0
	v_addc_co_u32_e32 v25, vcc, 0, v5, vcc
	v_add_co_u32_e32 v26, vcc, s2, v4
	s_mov_b32 s2, 0x240000
	s_nop 0
	v_addc_co_u32_e32 v27, vcc, 0, v5, vcc
	v_add_co_u32_e32 v28, vcc, s2, v4
	s_mov_b32 s2, 0x280000
	s_nop 0
	v_addc_co_u32_e32 v29, vcc, 0, v5, vcc
	v_add_co_u32_e32 v30, vcc, s2, v4
	s_mov_b32 s2, 0x2c0000
	s_nop 0
	v_addc_co_u32_e32 v31, vcc, 0, v5, vcc
	v_add_co_u32_e32 v32, vcc, s2, v4
	s_mov_b32 s2, 0x300000
	s_nop 0
	v_addc_co_u32_e32 v33, vcc, 0, v5, vcc
	v_add_co_u32_e32 v34, vcc, s2, v4
	s_mov_b32 s2, 0x340000
	s_nop 0
	v_addc_co_u32_e32 v35, vcc, 0, v5, vcc
	v_add_co_u32_e32 v36, vcc, s2, v4
	s_mov_b32 s2, 0x380000
	s_nop 0
	v_addc_co_u32_e32 v37, vcc, 0, v5, vcc
	v_add_co_u32_e32 v38, vcc, s2, v4
	s_mov_b32 s2, 0x3c0000
	s_nop 0
	v_addc_co_u32_e32 v39, vcc, 0, v5, vcc
	global_load_dwordx2 v[12:13], v[12:13], off
	s_mov_b32 s1, 0
	global_load_dwordx2 v[16:17], v[16:17], off
	v_lshl_add_u64 v[40:41], s[6:7], 0, v[2:3]
	global_load_dwordx2 v[20:21], v[20:21], off
	v_add_co_u32_e32 v4, vcc, s2, v4
	global_load_dwordx2 v[14:15], v[14:15], off
	s_nop 0
	v_addc_co_u32_e32 v5, vcc, 0, v5, vcc
	global_load_dwordx2 v[18:19], v[18:19], off
	s_nop 0
	global_load_dwordx2 v[22:23], v[22:23], off
	s_nop 0
	global_load_dwordx2 v[44:45], v[4:5], off
	v_mov_b32_e32 v4, 0
	global_load_dwordx2 v[24:25], v[24:25], off
	v_mov_b32_e32 v5, v4
	global_load_dwordx2 v[26:27], v[26:27], off
	v_mov_b32_e32 v2, v4
	global_load_dwordx2 v[28:29], v[28:29], off
	v_mov_b32_e32 v3, v4
	global_load_dwordx2 v[30:31], v[30:31], off
	v_mov_b32_e32 v7, v4
	global_load_dwordx2 v[32:33], v[32:33], off
	v_mov_b32_e32 v9, v4
	global_load_dwordx2 v[34:35], v[34:35], off
	v_mov_b32_e32 v78, v4
	global_load_dwordx2 v[36:37], v[36:37], off
	s_nop 0
	global_load_dwordx2 v[38:39], v[38:39], off
	s_waitcnt lgkmcnt(0)
	s_barrier
	s_branch .LBB0_773

; #define LAS __attribute__((address_space(3)))
; __global__ void __launch_bounds__(NTHREADS) fwd_megakernel(Params p) {
;     extern __shared__ __attribute__((aligned(16))) unsigned char lds_raw[];
;     LAS unsigned char* lds = (LAS unsigned char*)lds_raw;
	.amdhsa_kernel _Z14fwd_megakernel6Params
		.amdhsa_group_segment_fixed_size 0
		.amdhsa_private_segment_fixed_size 0
		.amdhsa_kernarg_size 384
		.amdhsa_user_sgpr_count 2
		.amdhsa_user_sgpr_dispatch_ptr 0
		.amdhsa_user_sgpr_queue_ptr 0
		.amdhsa_user_sgpr_kernarg_segment_ptr 1
		.amdhsa_user_sgpr_dispatch_id 0
		.amdhsa_user_sgpr_kernarg_preload_length 0
		.amdhsa_user_sgpr_kernarg_preload_offset 0
		.amdhsa_user_sgpr_private_segment_size 0
		.amdhsa_uses_dynamic_stack 0
		.amdhsa_enable_private_segment 0
		.amdhsa_system_sgpr_workgroup_id_x 1
		.amdhsa_system_sgpr_workgroup_id_y 0
		.amdhsa_system_sgpr_workgroup_id_z 0
		.amdhsa_system_sgpr_workgroup_info 0
		.amdhsa_system_vgpr_workitem_id 2
		.amdhsa_next_free_vgpr 255
		.amdhsa_next_free_sgpr 100
		.amdhsa_accum_offset 256
		.amdhsa_reserve_vcc 1
		.amdhsa_float_round_mode_32 0
		.amdhsa_float_round_mode_16_64 0
		.amdhsa_float_denorm_mode_32 3
		.amdhsa_float_denorm_mode_16_64 3
		.amdhsa_dx10_clamp 1
		.amdhsa_ieee_mode 1
		.amdhsa_fp16_overflow 0
		.amdhsa_tg_split 0
		.amdhsa_exception_fp_ieee_invalid_op 0
		.amdhsa_exception_fp_denorm_src 0
		.amdhsa_exception_fp_ieee_div_zero 0
		.amdhsa_exception_fp_ieee_overflow 0
		.amdhsa_exception_fp_ieee_underflow 0
		.amdhsa_exception_fp_ieee_inexact 0
		.amdhsa_exception_int_div_zero 0
	.end_amdhsa_kernel

; #define LAS __attribute__((address_space(3)))
; __global__ void __launch_bounds__(NTHREADS) fwd_megakernel(Params p) {
;     extern __shared__ __attribute__((aligned(16))) unsigned char lds_raw[];
;     LAS unsigned char* lds = (LAS unsigned char*)lds_raw;
amdhsa.kernels:
  - .agpr_count:     0
    .args:
      - .offset:         0
        .size:           128
        .value_kind:     by_value
      - .offset:         128
        .size:           4
        .value_kind:     hidden_block_count_x
      - .offset:         132
        .size:           4
        .value_kind:     hidden_block_count_y
      - .offset:         136
        .size:           4
        .value_kind:     hidden_block_count_z
      - .offset:         140
        .size:           2
        .value_kind:     hidden_group_size_x
      - .offset:         142
        .size:           2
        .value_kind:     hidden_group_size_y
      - .offset:         144
        .size:           2
        .value_kind:     hidden_group_size_z
      - .offset:         146
        .size:           2
        .value_kind:     hidden_remainder_x
      - .offset:         148
        .size:           2
        .value_kind:     hidden_remainder_y
      - .offset:         150
        .size:           2
        .value_kind:     hidden_remainder_z
      - .offset:         168
        .size:           8
        .value_kind:     hidden_global_offset_x
      - .offset:         176
        .size:           8
        .value_kind:     hidden_global_offset_y
      - .offset:         184
        .size:           8
        .value_kind:     hidden_global_offset_z
      - .offset:         192
        .size:           2
        .value_kind:     hidden_grid_dims
      - .offset:         216
        .size:           8
        .value_kind:     hidden_multigrid_sync_arg
      - .offset:         248
        .size:           4
        .value_kind:     hidden_dynamic_lds_size
    .group_segment_fixed_size: 0
    .kernarg_segment_align: 8
    .kernarg_segment_size: 384
    .language:       OpenCL C
    .language_version:
      - 2
      - 0
    .max_flat_workgroup_size: 512
    .name:           _Z14fwd_megakernel6Params
    .private_segment_fixed_size: 0
    .sgpr_count:     106
    .sgpr_spill_count: 176
    .symbol:         _Z14fwd_megakernel6Params.kd
    .uniform_work_group_size: 1
    .uses_dynamic_stack: false
    .vgpr_count:     255
    .vgpr_spill_count: 0
    .wavefront_size: 64
